# v33 + mLSTM next-chunk addresses derived from two computed addresses plus per-direction SGPR deltas (-32 VALU per step)
# speedup vs baseline: 1.0026x; 1.0002x over previous
; #define LAS __attribute__((address_space(3)))
; #define LBAR() do { asm volatile("s_waitcnt lgkmcnt(0)" ::: "memory"); __builtin_amdgcn_s_barrier(); asm volatile("" ::: "memory"); } while (0)
; #define GLOAD(c) do { const float* g0 = gates + MTOK((c) * 128 + 2 * lane) * 16; const float* g1 = gates + MTOK((c) * 128 + 2 * lane + 1) * 16; \
;                 gi0 = g0[gcol]; gf0 = g0[gcol + 4]; gi1 = g1[gcol]; gf1 = g1[gcol + 4]; } while (0)
; DI void mlstm_phase(LAS unsigned char* lds, const bf16_t* proj, const float* gates, bf16_t* Hfw, bf16_t* Hbw, int G, int bid) {
;     ...
;         const int it_ = item & 255; const bool lng = item < 256;
;         const int it = ((((it_ >> 3) >> 2) * 8 + (it_ & 7)) << 2) | ((it_ >> 3) & 3);
;         const int sl = it & 3, dir = (it >> 2) & 1, hh = (it >> 3) & 3, b = it >> 5;
;         const int S = lng ? 8192 : 4096; const int tok0 = lng ? b * 8192 : TP + b * 4096; const int nc = S >> 7;
;         bf16_t* Hout = dir ? Hbw : Hfw;
;         const int gcol = dir * 8 + hh;
;         LBAR();
;         for (int i = tid; i < 80 * MQ_STRIDE / 4; i += 512) ((LAS unsigned*)Cs)[i] = 0u;
;         if (tid < 128) { LAS unsigned* p = (LAS unsigned*)(Vs + tid * MV_STRIDE + 128); unsigned z = 0u; asm volatile("" : "+v"(z)); p[0] = 0x3F80u | z;
; #pragma unroll
;             for (int i = 1; i < 8; ++i) p[i] = z; }
;         const int nown = (wid < 2) ? 2 : ((wid < 6) ? 1 : 0);
;         f32x4 Creg[2][5];
; #pragma unroll
;         for (int dt = 0; dt < 5; ++dt) { Creg[0][dt] = (f32x4){0.f, 0.f, 0.f, 0.f}; Creg[1][dt] = Creg[0][dt]; }
;         float mprev = 0.f;
;         u32x4 pq[4], pk[4], pv[2]; float gi0 = 0.f, gi1 = 0.f, gf0 = 0.f, gf1 = 0.f;
;     ...
;         MLOAD(0);
;         if (wid == 2) { GLOAD(0); GATES(0); }
.LBB0_828:
	s_or_b64 exec, exec, s[38:39]
	s_bfe_u32 s36, s48, 0x30005
	s_lshl_b32 s38, s36, 13
	s_lshl_b32 s36, s36, 12
	s_and_b32 s50, s48, 1
	s_bfe_u32 s47, s48, 0x20001
	s_bitset1_b32 s36, 16
	s_cmpk_lt_i32 s48, 0x100
	s_movk_i32 s39, 0x2000
	s_cselect_b32 s46, s39, 0x1000
	s_cselect_b32 s96, s38, s36
	s_cmp_eq_u32 s50, 0
	v_not_b32_e32 v0, v155
	v_add_u32_e32 v0, s46, v0
	s_cselect_b64 s[90:91], -1, 0
	s_mov_b32 s98, 0xfffd0000
	s_mov_b32 s100, 0xfffa0000
	s_cselect_b32 s98, 0x30000, s98
	s_cselect_b32 s99, 0, -1
	s_cselect_b32 s100, 0x60000, s100
	s_cselect_b32 s101, 0, -1
	v_readlane_b32 s38, v255, 20
	v_cndmask_b32_e64 v0, v0, v155, s[90:91]
	v_readlane_b32 s39, v255, 21
	v_add_u32_e32 v0, s96, v0
	v_writelane_b32 v255, s48, 22
	v_mov_b64_e32 v[2:3], s[38:39]
	s_waitcnt vmcnt(11)
	v_mad_i64_i32 v[4:5], s[38:39], v0, s33, v[2:3]
	v_not_b32_e32 v0, v156
	v_add_u32_e32 v0, s46, v0
	v_cndmask_b32_e64 v0, v0, v156, s[90:91]
	v_add_u32_e32 v0, s96, v0
	s_waitcnt vmcnt(9)
	v_mad_i64_i32 v[12:13], s[38:39], v0, s33, v[2:3]
	v_not_b32_e32 v0, v157
	v_add_u32_e32 v0, s46, v0
	v_cndmask_b32_e64 v0, v0, v157, s[90:91]
	v_add_u32_e32 v0, s96, v0
	s_waitcnt vmcnt(7)
	v_mad_i64_i32 v[20:21], s[38:39], v0, s33, v[2:3]
	v_not_b32_e32 v0, v158
	v_add_u32_e32 v0, s46, v0
	v_cndmask_b32_e64 v0, v0, v158, s[90:91]
	v_add_u32_e32 v0, s96, v0
	s_waitcnt vmcnt(5)
	v_mad_i64_i32 v[28:29], s[38:39], v0, s33, v[2:3]
	v_not_b32_e32 v0, v159
	v_add_u32_e32 v0, s46, v0
	v_cndmask_b32_e64 v0, v0, v159, s[90:91]
	s_lshl_b32 s38, s48, 3
	v_add_u32_e32 v0, s96, v0
	s_and_b32 s48, s38, 0xc0
	s_waitcnt vmcnt(3)
	v_mad_i64_i32 v[36:37], s[38:39], v0, s33, v[2:3]
	v_not_b32_e32 v0, v160
	v_add_u32_e32 v0, s46, v0
	v_cndmask_b32_e64 v0, v0, v160, s[90:91]
	s_lshl_b32 s40, s47, 9
	s_mov_b32 s41, s37
	v_add_u32_e32 v0, s96, v0
	s_lshl_b32 s36, s47, 8
	v_lshl_add_u64 v[36:37], v[36:37], 0, s[40:41]
	s_lshl_b32 s38, s48, 1
	s_mov_b32 s39, s37
	v_mad_i64_i32 v[2:3], s[48:49], v0, s33, v[2:3]
	v_lshl_add_u64 v[4:5], v[4:5], 0, s[36:37]
	v_mov_b32_e32 v123, v1
	v_lshl_add_u64 v[12:13], v[12:13], 0, s[36:37]
	v_lshl_add_u64 v[20:21], v[20:21], 0, s[36:37]
	v_lshl_add_u64 v[28:29], v[28:29], 0, s[36:37]
	v_lshl_add_u64 v[36:37], v[36:37], 0, s[38:39]
	v_mov_b32_e32 v125, v1
	v_lshl_add_u64 v[2:3], v[2:3], 0, s[40:41]
	v_lshl_add_u64 v[8:9], v[4:5], 0, v[122:123]
	v_lshl_add_u64 v[16:17], v[12:13], 0, v[122:123]
	v_lshl_add_u64 v[24:25], v[20:21], 0, v[122:123]
	v_lshl_add_u64 v[32:33], v[28:29], 0, v[122:123]
	v_lshl_add_u64 v[36:37], v[36:37], 0, v[124:125]
	v_lshl_add_u64 v[2:3], v[2:3], 0, s[38:39]
	global_load_dwordx4 v[4:7], v[8:9], off
	s_nop 0
	global_load_dwordx4 v[8:11], v[8:9], off offset:1024
	s_nop 0
	global_load_dwordx4 v[12:15], v[16:17], off
	s_nop 0
	global_load_dwordx4 v[16:19], v[16:17], off offset:1024
	s_nop 0
	global_load_dwordx4 v[20:23], v[24:25], off
	s_nop 0
	global_load_dwordx4 v[24:27], v[24:25], off offset:1024
	s_nop 0
	global_load_dwordx4 v[28:31], v[32:33], off
	s_nop 0
	global_load_dwordx4 v[32:35], v[32:33], off offset:1024
	v_lshl_add_u64 v[2:3], v[2:3], 0, v[124:125]
	global_load_dwordx4 v[36:39], v[36:37], off offset:2048
	s_nop 0
	global_load_dwordx4 v[40:43], v[2:3], off offset:2048
	s_lshl_b32 s39, s50, 3
	s_or_b32 s39, s39, s47
	s_and_b64 vcc, exec, s[0:1]
	s_cbranch_vccz .LBB0_832
	v_not_b32_e32 v0, v144
	v_add_u32_e32 v0, s46, v0
	v_cndmask_b32_e64 v0, v0, v144, s[90:91]
	v_add_u32_e32 v0, s96, v0
	v_lshlrev_b64 v[2:3], 6, v[0:1]
	v_readlane_b32 s48, v255, 26
	v_sub_u32_e32 v0, s46, v144
	v_readlane_b32 s49, v255, 27
	v_add_u32_e32 v0, -2, v0
	v_or_b32_e32 v44, 1, v144
	v_lshl_add_u64 v[2:3], s[48:49], 0, v[2:3]
	v_cndmask_b32_e64 v0, v0, v44, s[90:91]
	s_lshl_b32 s40, s39, 2
	s_mov_b32 s41, s37
	v_add_u32_e32 v0, s96, v0
	v_lshl_add_u64 v[2:3], v[2:3], 0, s[40:41]
	global_load_dword v123, v[2:3], off offset:16
	v_lshlrev_b64 v[44:45], 6, v[0:1]
	v_lshl_add_u64 v[44:45], s[48:49], 0, v[44:45]
	v_lshl_add_u64 v[44:45], v[44:45], 0, s[40:41]
	global_load_dword v207, v[44:45], off offset:16
	global_load_dword v133, v[44:45], off
	global_load_dword v132, v[2:3], off
	s_mov_b32 s40, 0xb102e308
	s_waitcnt vmcnt(3)
	v_max_f32_e32 v0, v123, v123
	v_mul_f32_e64 v3, |v123|, s35
	v_min_f32_e32 v2, 0, v0
	v_exp_f32_e32 v0, v3
	s_waitcnt vmcnt(2)
; DI float logsig(float x) { return fminf(x, 0.f) - log1pf(__expf(-fabsf(x))); }
	v_mul_f32_e64 v44, |v207|, s35
	v_exp_f32_e32 v80, v44
	v_max_f32_e32 v3, v207, v207
	v_add_f32_e32 v46, 1.0, v0
	v_frexp_mant_f32_e32 v48, v46
	v_cvt_f64_f32_e32 v[44:45], v46
	v_add_f32_e32 v49, 1.0, v80
	v_add_f32_e32 v47, -1.0, v46
	v_frexp_exp_i32_f64_e32 v51, v[44:45]
	v_cvt_f64_f32_e32 v[44:45], v49
	v_cmp_gt_f32_e32 vcc, s42, v48
	v_sub_f32_e32 v50, v47, v46
	v_add_f32_e32 v52, -1.0, v49
	v_frexp_mant_f32_e32 v53, v49
	v_frexp_exp_i32_f64_e32 v44, v[44:45]
	v_subbrev_co_u32_e32 v45, vcc, 0, v51, vcc
	v_sub_f32_e32 v47, v0, v47
	v_add_f32_e32 v50, 1.0, v50
	v_sub_f32_e32 v54, v52, v49
	v_cmp_gt_f32_e32 vcc, s42, v53
	v_sub_f32_e32 v52, v80, v52
	v_add_f32_e32 v47, v47, v50
	v_add_f32_e32 v48, 1.0, v54
	v_subbrev_co_u32_e32 v50, vcc, 0, v44, vcc
	v_sub_u32_e32 v51, 0, v45
	v_add_f32_e32 v52, v52, v48
	v_ldexp_f32 v46, v46, v51
	v_ldexp_f32 v48, v47, v51
	v_sub_u32_e32 v51, 0, v50
	v_cvt_f32_i32_e32 v44, v45
	v_cvt_f32_i32_e32 v45, v50
	v_ldexp_f32 v47, v49, v51
	v_ldexp_f32 v49, v52, v51
	v_pk_add_f32 v[50:51], v[46:47], 1.0 op_sel_hi:[1,0]
	v_pk_add_f32 v[52:53], v[46:47], -1.0 op_sel_hi:[1,0]
	v_pk_add_f32 v[54:55], v[50:51], -1.0 op_sel_hi:[1,0]
	v_pk_add_f32 v[56:57], v[52:53], 1.0 op_sel_hi:[1,0]
	v_pk_add_f32 v[54:55], v[46:47], v[54:55] neg_lo:[0,1] neg_hi:[0,1]
	v_pk_add_f32 v[46:47], v[46:47], v[56:57] neg_lo:[0,1] neg_hi:[0,1]
	v_pk_mul_f32 v[56:57], v[44:45], s[34:35] op_sel_hi:[1,0]
	v_pk_add_f32 v[54:55], v[48:49], v[54:55]
	v_pk_add_f32 v[46:47], v[48:49], v[46:47]
	v_pk_fma_f32 v[48:49], v[44:45], s[34:35], v[56:57] op_sel_hi:[1,0,1] neg_lo:[0,0,1] neg_hi:[0,0,1]
	v_pk_add_f32 v[62:63], v[50:51], v[54:55]
	v_pk_fma_f32 v[44:45], v[44:45], s[40:41], v[48:49] op_sel_hi:[1,0,1]
	v_rcp_f32_e32 v48, v62
	v_rcp_f32_e32 v49, v63
	v_pk_add_f32 v[64:65], v[52:53], v[46:47]
	v_pk_add_f32 v[50:51], v[62:63], v[50:51] neg_lo:[0,1] neg_hi:[0,1]
	v_pk_add_f32 v[52:53], v[64:65], v[52:53] neg_lo:[0,1] neg_hi:[0,1]
	v_pk_add_f32 v[50:51], v[54:55], v[50:51] neg_lo:[0,1] neg_hi:[0,1]
	v_pk_mul_f32 v[54:55], v[64:65], v[48:49]
	v_pk_add_f32 v[46:47], v[46:47], v[52:53] neg_lo:[0,1] neg_hi:[0,1]
	v_pk_mul_f32 v[72:73], v[62:63], v[54:55]
	s_mov_b32 s40, 0x3e9b6dac
	v_pk_fma_f32 v[74:75], v[54:55], v[62:63], v[72:73] neg_lo:[0,0,1] neg_hi:[0,0,1]
	v_pk_add_f32 v[66:67], v[56:57], v[44:45]
	v_pk_fma_f32 v[74:75], v[54:55], v[50:51], v[74:75]
	v_mov_b32_e32 v61, v57
	v_pk_add_f32 v[76:77], v[72:73], v[74:75]
	v_mov_b32_e32 v71, v45
	v_pk_add_f32 v[78:79], v[64:65], v[76:77] neg_lo:[0,1] neg_hi:[0,1]
	v_pk_add_f32 v[72:73], v[76:77], v[72:73] neg_lo:[0,1] neg_hi:[0,1]
	v_pk_add_f32 v[64:65], v[64:65], v[78:79] neg_lo:[0,1] neg_hi:[0,1]
	v_pk_add_f32 v[72:73], v[72:73], v[74:75] neg_lo:[0,1] neg_hi:[0,1]
	v_pk_add_f32 v[64:65], v[64:65], v[76:77] neg_lo:[0,1] neg_hi:[0,1]
	v_mov_b32_e32 v60, v66
	v_pk_add_f32 v[46:47], v[46:47], v[64:65]
	v_mov_b32_e32 v52, v66
	v_pk_add_f32 v[46:47], v[72:73], v[46:47]
	v_mov_b32_e32 v58, v56
	v_pk_add_f32 v[64:65], v[78:79], v[46:47]
	v_mov_b32_e32 v68, v44
	v_pk_mul_f32 v[72:73], v[48:49], v[64:65]
	v_pk_add_f32 v[74:75], v[78:79], v[64:65] neg_lo:[0,1] neg_hi:[0,1]
	v_pk_mul_f32 v[76:77], v[62:63], v[72:73]
	v_pk_add_f32 v[46:47], v[46:47], v[74:75]
	v_pk_fma_f32 v[62:63], v[72:73], v[62:63], v[76:77] neg_lo:[0,0,1] neg_hi:[0,0,1]
	v_pk_add_f32 v[74:75], v[54:55], v[72:73]
	v_pk_fma_f32 v[50:51], v[72:73], v[50:51], v[62:63]
	v_pk_add_f32 v[54:55], v[74:75], v[54:55] neg_lo:[0,1] neg_hi:[0,1]
	v_pk_add_f32 v[62:63], v[76:77], v[50:51]
	v_pk_add_f32 v[54:55], v[72:73], v[54:55] neg_lo:[0,1] neg_hi:[0,1]
	v_pk_add_f32 v[72:73], v[62:63], v[76:77] neg_lo:[0,1] neg_hi:[0,1]
	v_pk_add_f32 v[76:77], v[64:65], v[62:63] neg_lo:[0,1] neg_hi:[0,1]
	v_pk_add_f32 v[50:51], v[72:73], v[50:51] neg_lo:[0,1] neg_hi:[0,1]
	v_pk_add_f32 v[64:65], v[64:65], v[76:77] neg_lo:[0,1] neg_hi:[0,1]
	v_cmp_neq_f32_e32 vcc, s43, v0
	v_pk_add_f32 v[62:63], v[64:65], v[62:63] neg_lo:[0,1] neg_hi:[0,1]
	v_min_f32_e32 v3, 0, v3
	v_pk_add_f32 v[46:47], v[46:47], v[62:63]
	s_nop 0
	v_pk_add_f32 v[46:47], v[50:51], v[46:47]
	s_nop 0
	v_pk_add_f32 v[46:47], v[76:77], v[46:47]
	s_nop 0
	v_pk_mul_f32 v[46:47], v[48:49], v[46:47]
	s_nop 0
	v_pk_add_f32 v[46:47], v[54:55], v[46:47]
	s_nop 0
	v_pk_add_f32 v[48:49], v[74:75], v[46:47]
	s_nop 0
	v_pk_add_f32 v[50:51], v[48:49], v[74:75] neg_lo:[0,1] neg_hi:[0,1]
	v_pk_mul_f32 v[62:63], v[48:49], v[48:49]
	v_pk_add_f32 v[46:47], v[46:47], v[50:51] neg_lo:[0,1] neg_hi:[0,1]
	v_pk_fma_f32 v[50:51], v[62:63], s[40:41], v[130:131] op_sel_hi:[1,0,0]
	s_mov_b32 s40, 0x3f2aaada
	v_ldexp_f32 v54, v48, 1
	v_ldexp_f32 v55, v49, 1
	v_pk_mul_f32 v[48:49], v[48:49], v[62:63]
	v_pk_fma_f32 v[50:51], v[62:63], v[50:51], s[40:41] op_sel_hi:[1,1,0]
	v_ldexp_f32 v69, v47, 1
	v_pk_mul_f32 v[48:49], v[48:49], v[50:51]
	v_ldexp_f32 v46, v46, 1
	v_pk_add_f32 v[50:51], v[54:55], v[48:49]
	v_mov_b32_e32 v47, v69
	v_pk_add_f32 v[54:55], v[50:51], v[54:55] neg_lo:[0,1] neg_hi:[0,1]
	v_mov_b32_e32 v53, v51
	v_pk_add_f32 v[48:49], v[48:49], v[54:55] neg_lo:[0,1] neg_hi:[0,1]
	s_nop 0
	v_pk_add_f32 v[54:55], v[46:47], v[48:49]
	v_mov_b32_e32 v59, v49
	v_pk_add_f32 v[62:63], v[50:51], v[54:55]
	v_mov_b32_e32 v49, v51
	v_mov_b32_e32 v47, v55
	v_mov_b32_e32 v70, v62
	v_pk_add_f32 v[46:47], v[46:47], v[48:49]
	v_pk_add_f32 v[48:49], v[60:61], v[70:71]
	v_mov_b32_e32 v64, v62
	v_mov_b32_e32 v65, v55
	v_pk_add_f32 v[52:53], v[52:53], v[64:65]
	v_pk_add_f32 v[64:65], v[66:67], v[62:63]
	v_pk_add_f32 v[48:49], v[48:49], v[60:61] neg_lo:[0,1] neg_hi:[0,1]
	v_pk_add_f32 v[58:59], v[58:59], v[68:69]
; DI float logsig(float x) { return fminf(x, 0.f) - log1pf(__expf(-fabsf(x))); }
	v_pk_add_f32 v[60:61], v[70:71], v[48:49] neg_lo:[0,1] neg_hi:[0,1]
	v_mov_b32_e32 v68, v62
	v_mov_b32_e32 v69, v65
	v_mov_b32_e32 v70, v50
	v_mov_b32_e32 v71, v67
	v_pk_add_f32 v[68:69], v[68:69], v[70:71] neg_lo:[0,1] neg_hi:[0,1]
	v_mov_b32_e32 v70, v66
	v_mov_b32_e32 v71, v65
	v_mov_b32_e32 v57, v69
	v_pk_add_f32 v[56:57], v[70:71], v[56:57] neg_lo:[0,1] neg_hi:[0,1]
	v_mov_b32_e32 v71, v49
	v_mov_b32_e32 v70, v56
	v_mov_b32_e32 v49, v51
	v_pk_add_f32 v[70:71], v[44:45], v[70:71] neg_lo:[0,1] neg_hi:[0,1]
	v_pk_add_f32 v[48:49], v[52:53], v[48:49] neg_lo:[0,1] neg_hi:[0,1]
	v_mov_b32_e32 v45, v67
	v_pk_add_f32 v[48:49], v[58:59], v[48:49] neg_lo:[0,1] neg_hi:[0,1]
	v_pk_add_f32 v[44:45], v[44:45], v[56:57] neg_lo:[0,1] neg_hi:[0,1]
	v_pk_add_f32 v[46:47], v[46:47], v[68:69] neg_lo:[0,1] neg_hi:[0,1]
	v_pk_add_f32 v[50:51], v[62:63], v[50:51] neg_lo:[0,1] neg_hi:[0,1]
	v_pk_add_f32 v[52:53], v[46:47], v[44:45]
	v_mov_b32_e32 v47, v49
	v_pk_add_f32 v[50:51], v[54:55], v[50:51] neg_lo:[0,1] neg_hi:[0,1]
	v_pk_add_f32 v[54:55], v[60:61], v[48:49]
	v_pk_add_f32 v[46:47], v[70:71], v[46:47]
	v_mov_b32_e32 v45, v61
	v_pk_add_f32 v[46:47], v[46:47], v[44:45] neg_lo:[0,1] neg_hi:[0,1]
	v_mov_b32_e32 v48, v52
	v_mov_b32_e32 v49, v55
	v_pk_add_f32 v[48:49], v[48:49], v[46:47] neg_lo:[0,1] neg_hi:[0,1]
	v_pk_add_f32 v[46:47], v[50:51], v[46:47] neg_lo:[0,1] neg_hi:[0,1]
	v_pk_add_f32 v[44:45], v[44:45], v[48:49] neg_lo:[0,1] neg_hi:[0,1]
	s_nop 0
	v_pk_add_f32 v[44:45], v[46:47], v[44:45]
	v_pk_add_f32 v[46:47], v[54:55], v[52:53]
	s_nop 0
	v_pk_add_f32 v[48:49], v[64:65], v[46:47]
	s_nop 0
	v_pk_add_f32 v[50:51], v[48:49], v[64:65] neg_lo:[0,1] neg_hi:[0,1]
	s_nop 0
	v_pk_add_f32 v[46:47], v[46:47], v[50:51] neg_lo:[0,1] neg_hi:[0,1]
	s_nop 0
	v_pk_add_f32 v[44:45], v[44:45], v[46:47]
	s_nop 0
	v_pk_add_f32 v[44:45], v[48:49], v[44:45]
	s_nop 0
	v_cndmask_b32_e32 v44, v201, v44, vcc
	v_cmp_neq_f32_e32 vcc, s43, v80
	s_nop 1
	v_cndmask_b32_e32 v45, v201, v45, vcc
	v_cmp_ngt_f32_e32 vcc, -1.0, v80
	s_nop 1
	v_cndmask_b32_e32 v45, v202, v45, vcc
	v_cmp_ngt_f32_e32 vcc, -1.0, v0
	s_nop 1
	v_cndmask_b32_e32 v44, v202, v44, vcc
	v_cmp_neq_f32_e32 vcc, -1.0, v0
	s_nop 1
	v_cndmask_b32_e32 v44, v203, v44, vcc
	v_cmp_neq_f32_e32 vcc, -1.0, v80
	s_nop 1
	v_cndmask_b32_e32 v45, v203, v45, vcc
	v_cmp_lt_f32_e64 vcc, |v80|, s44
	s_nop 1
	v_cndmask_b32_e32 v45, v45, v80, vcc
	v_cmp_lt_f32_e64 vcc, |v0|, s44
	s_nop 1
	v_cndmask_b32_e32 v44, v44, v0, vcc
	v_pk_add_f32 v[2:3], v[2:3], v[44:45] neg_lo:[0,1] neg_hi:[0,1]
	v_add_u32_e32 v44, -1, v193
	v_add_f32_e32 v0, v2, v3
	v_and_b32_e32 v3, 64, v193
	v_cmp_lt_i32_e32 vcc, v44, v3
	v_add_u32_e32 v45, -2, v193
	s_nop 0
	v_cndmask_b32_e32 v44, v44, v193, vcc
	v_lshlrev_b32_e32 v48, 2, v44
	ds_bpermute_b32 v44, v48, v0
	v_cmp_lt_i32_e32 vcc, v45, v3
	s_waitcnt lgkmcnt(0)
	v_add_f32_e32 v44, v0, v44
	v_cndmask_b32_e32 v45, v45, v193, vcc
	v_cndmask_b32_e64 v44, v44, v0, s[8:9]
	v_lshlrev_b32_e32 v49, 2, v45
	ds_bpermute_b32 v45, v49, v44
	s_waitcnt lgkmcnt(0)
	v_add_f32_e32 v45, v44, v45
	v_cndmask_b32_e64 v44, v45, v44, s[14:15]
	v_add_u32_e32 v45, -4, v193
	v_cmp_lt_i32_e32 vcc, v45, v3
	s_nop 1
	v_cndmask_b32_e32 v45, v45, v193, vcc
	v_lshlrev_b32_e32 v50, 2, v45
	ds_bpermute_b32 v45, v50, v44
	s_waitcnt lgkmcnt(0)
	v_add_f32_e32 v45, v44, v45
	v_cndmask_b32_e64 v44, v45, v44, s[16:17]
	v_add_u32_e32 v45, -8, v193
	v_cmp_lt_i32_e32 vcc, v45, v3
	s_nop 1
	v_cndmask_b32_e32 v45, v45, v193, vcc
	v_lshlrev_b32_e32 v51, 2, v45
	ds_bpermute_b32 v45, v51, v44
	s_waitcnt lgkmcnt(0)
	v_add_f32_e32 v45, v44, v45
	v_cndmask_b32_e64 v44, v45, v44, s[18:19]
	v_add_u32_e32 v45, -16, v193
	v_cmp_lt_i32_e32 vcc, v45, v3
	s_nop 1
	v_cndmask_b32_e32 v45, v45, v193, vcc
	v_lshlrev_b32_e32 v52, 2, v45
	ds_bpermute_b32 v45, v52, v44
	s_waitcnt lgkmcnt(0)
	v_add_f32_e32 v45, v44, v45
	v_cndmask_b32_e64 v44, v45, v44, s[20:21]
	v_subrev_u32_e32 v45, 32, v193
	v_cmp_lt_i32_e32 vcc, v45, v3
	s_nop 1
	v_cndmask_b32_e32 v3, v45, v193, vcc
	v_lshlrev_b32_e32 v3, 2, v3
	ds_bpermute_b32 v45, v3, v44
	s_waitcnt lgkmcnt(0)
	v_add_f32_e32 v45, v44, v45
	v_cndmask_b32_e64 v45, v45, v44, s[22:23]
	v_sub_f32_e32 v0, v45, v0
	v_add_f32_e32 v44, v2, v0
	s_waitcnt vmcnt(0)
	v_pk_add_f32 v[46:47], v[132:133], v[44:45] neg_lo:[0,1] neg_hi:[0,1]
	s_nop 0
	v_max_f32_e32 v0, v46, v47
	ds_bpermute_b32 v2, v48, v0
	s_waitcnt lgkmcnt(0)
	v_max_f32_e32 v2, v2, v2
	v_max_f32_e32 v2, v0, v2
	v_cndmask_b32_e64 v0, v2, v0, s[8:9]
	ds_bpermute_b32 v2, v49, v0
	s_waitcnt lgkmcnt(0)
	v_max_f32_e32 v2, v2, v2
	v_max_f32_e32 v2, v0, v2
	v_cndmask_b32_e64 v0, v2, v0, s[14:15]
	ds_bpermute_b32 v2, v50, v0
	s_waitcnt lgkmcnt(0)
	v_max_f32_e32 v2, v2, v2
	v_max_f32_e32 v2, v0, v2
	v_cndmask_b32_e64 v0, v2, v0, s[16:17]
	ds_bpermute_b32 v2, v51, v0
	s_waitcnt lgkmcnt(0)
	v_max_f32_e32 v2, v2, v2
	v_max_f32_e32 v2, v0, v2
	v_cndmask_b32_e64 v0, v2, v0, s[18:19]
	ds_bpermute_b32 v2, v52, v0
	s_waitcnt lgkmcnt(0)
	v_max_f32_e32 v2, v2, v2
	v_max_f32_e32 v2, v0, v2
	v_cndmask_b32_e64 v0, v2, v0, s[20:21]
	ds_bpermute_b32 v2, v3, v0
	v_max_f32_e32 v3, v0, v0
	s_waitcnt lgkmcnt(0)
	v_max_f32_e32 v2, v2, v2
	v_max_f32_e32 v2, v3, v2
	v_cndmask_b32_e64 v0, v2, v0, s[22:23]
	ds_bpermute_b32 v2, v48, v0
	v_max_f32_e32 v0, v0, v0
	v_max_f32_e32 v49, 0, v0
	v_lshl_or_b32 v0, v193, 2, v205
	ds_bpermute_b32 v3, v0, v49
	ds_bpermute_b32 v0, v0, v45
	s_waitcnt lgkmcnt(2)
	v_cndmask_b32_e64 v2, v2, v204, s[8:9]
	v_max3_f32 v48, v2, v46, 0
	ds_write_b64 v145, v[46:47]
	ds_write_b64 v189, v[48:49]
	ds_write_b64 v187, v[44:45]
	s_and_saveexec_b64 s[40:41], s[8:9]
	s_cbranch_execz .LBB0_831
	v_readlane_b32 s48, v255, 39
	v_mov_b32_e32 v2, v1
	s_nop 0
	v_mov_b32_e32 v44, s48
	s_waitcnt lgkmcnt(4)
	ds_write_b64 v44, v[2:3]

; #define LAS __attribute__((address_space(3)))
; DI unsigned pk2(float lo, float hi) { f32x2 v = {lo, hi}; bf16x2_t b = __builtin_convertvector(v, bf16x2_t); return __builtin_bit_cast(unsigned, b); }
; DI float bflo(unsigned u) { return __uint_as_float(u << 16); }
; DI float bfhi(unsigned u) { return __uint_as_float(u & 0xffff0000u); }
; #define GLOAD(c) do { const float* g0 = gates + MTOK((c) * 128 + 2 * lane) * 16; const float* g1 = gates + MTOK((c) * 128 + 2 * lane + 1) * 16; \
;                 gi0 = g0[gcol]; gf0 = g0[gcol + 4]; gi1 = g1[gcol]; gf1 = g1[gcol + 4]; } while (0)
; DI void mlstm_phase(LAS unsigned char* lds, const bf16_t* proj, const float* gates, bf16_t* Hfw, bf16_t* Hbw, int G, int bid) {
;     ...
;             LAS float* sa = smal + cur * 388; LAS float* sM = sa + 128; LAS float* sb = sa + 256; LAS float* scl = sa + 384;
;             const float mp = scl[0], M127 = scl[1];
; #pragma unroll
;             for (int i = 0; i < 4; ++i) { const int ci = tid + 512 * i, row = ci >> 4, ch = ci & 15;
;                 *(LAS u32x4*)(Qs + row * MQ_STRIDE + ch * 16) = pq[i]; *(LAS u32x4*)(Ks + row * MQ_STRIDE + ch * 16) = pk[i]; }
; #pragma unroll
;             for (int i = 0; i < 2; ++i) { const int ci = tid + 512 * i, row = ci >> 3, ch = ci & 7;
;                 *(LAS u32x4*)(Vs + row * MV_STRIDE + ch * 16) = pv[i];
;                 const float wsv = __expf(sa[row] - M127);
;                 u32x4 w;
; #pragma unroll
;                 for (int e = 0; e < 4; ++e) w[e] = pk2(bflo(pv[i][e]) * wsv, bfhi(pv[i][e]) * wsv);
;                 *(LAS u32x4*)(VWs + row * MV_STRIDE + ch * 16) = w;
;                 if (ch == 0) { const u32x4 x0 = {pk2(wsv, 0.f), 0u, 0u, 0u}, x1 = {0u, 0u, 0u, 0u};
;                     *(LAS u32x4*)(VWs + row * MV_STRIDE + 128) = x0; *(LAS u32x4*)(VWs + row * MV_STRIDE + 144) = x1; }
;             }
;             if (c + 1 < nc) { MLOAD(c + 1); if (wid == 2) GLOAD(c + 1); }
.LBB0_836:
	v_add_u32_e32 v0, 0x80, v155
	v_sub_u32_e32 v2, 0xffffff7f, v155
	v_add_u32_e32 v0, s48, v0
	v_add_u32_e32 v2, s46, v2
	v_cndmask_b32_e64 v2, v2, v0, s[90:91]
	v_ashrrev_i32_e32 v3, 31, v2
	v_lshl_add_u64 v[2:3], v[2:3], 0, s[96:97]
	v_mad_u64_u32 v[212:213], s[92:93], v2, s33, v[138:139]
	v_add_u32_e32 v0, 0x80, v159
	v_mad_i32_i24 v213, v3, s33, v213
	v_sub_u32_e32 v2, 0xffffff7f, v159
	v_add_u32_e32 v0, s48, v0
	v_add_u32_e32 v2, s46, v2
	v_cndmask_b32_e64 v2, v2, v0, s[90:91]
	v_ashrrev_i32_e32 v3, 31, v2
	v_lshl_add_u64 v[2:3], v[2:3], 0, s[96:97]
	v_mad_u64_u32 v[220:221], s[92:93], v2, s33, v[140:141]
	v_lshl_add_u64 v[214:215], v[212:213], 0, s[98:99]
	v_mad_i32_i24 v221, v3, s33, v221
	v_lshl_add_u64 v[216:217], v[214:215], 0, s[98:99]
	v_lshl_add_u64 v[218:219], v[216:217], 0, s[98:99]
	v_lshl_add_u64 v[222:223], v[220:221], 0, s[100:101]
	s_and_b32 s50, s49, 1
	s_mul_i32 s40, s50, 0x610
	s_add_i32 s51, s40, 0
	s_add_i32 s51, s51, 0x20500
	v_mov_b32_e32 v0, s51
	ds_read_b64 v[142:143], v0 offset:1536
	v_lshl_add_u32 v224, v159, 2, s51
	v_lshl_add_u32 v225, v160, 2, s51
	ds_read_b32 v224, v224
	ds_read_b32 v225, v225
	v_add_u32_e32 v0, v149, v161
	s_waitcnt vmcnt(9)
	ds_write_b128 v179, v[4:7]
	s_waitcnt vmcnt(8)
	ds_write_b128 v179, v[8:11] offset:34816
	global_load_dwordx4 v[4:7], v[212:213], off
	global_load_dwordx4 v[8:11], v[212:213], off offset:1024
	s_waitcnt vmcnt(9)
	ds_write_b128 v180, v[12:15]
	s_waitcnt vmcnt(8)
	ds_write_b128 v180, v[16:19] offset:34816
	global_load_dwordx4 v[12:15], v[214:215], off
	global_load_dwordx4 v[16:19], v[214:215], off offset:1024
	s_waitcnt vmcnt(9)
	ds_write_b128 v181, v[20:23]
	s_waitcnt vmcnt(8)
	ds_write_b128 v181, v[24:27] offset:34816
	global_load_dwordx4 v[20:23], v[216:217], off
	global_load_dwordx4 v[24:27], v[216:217], off offset:1024
	s_waitcnt vmcnt(9)
	ds_write_b128 v182, v[28:31]
	s_waitcnt vmcnt(8)
	ds_write_b128 v182, v[32:35] offset:34816
	global_load_dwordx4 v[28:31], v[218:219], off
	global_load_dwordx4 v[32:35], v[218:219], off offset:1024
	s_waitcnt vmcnt(9)
	ds_write_b128 v0, v[36:39]
	v_lshlrev_b32_e32 v2, 16, v36
	v_and_b32_e32 v3, 0xffff0000, v36
	s_waitcnt lgkmcnt(9)
	v_sub_f32_e32 v0, v224, v143
	v_mul_f32_e32 v0, 0x3fb8aa3b, v0
	v_exp_f32_e32 v0, v0
	s_nop 0
	v_pk_mul_f32 v[2:3], v[0:1], v[2:3] op_sel_hi:[0,1]
	v_cvt_pk_bf16_f32 v84, v2, v3
	v_lshlrev_b32_e32 v2, 16, v37
	v_and_b32_e32 v3, 0xffff0000, v37
	v_pk_mul_f32 v[2:3], v[0:1], v[2:3] op_sel_hi:[0,1]
	v_cvt_pk_bf16_f32 v85, v2, v3
	v_lshlrev_b32_e32 v2, 16, v38
	v_and_b32_e32 v3, 0xffff0000, v38
	v_pk_mul_f32 v[2:3], v[0:1], v[2:3] op_sel_hi:[0,1]
	v_cvt_pk_bf16_f32 v86, v2, v3
	v_lshlrev_b32_e32 v2, 16, v39
	v_and_b32_e32 v3, 0xffff0000, v39
	v_pk_mul_f32 v[2:3], v[0:1], v[2:3] op_sel_hi:[0,1]
	v_cvt_pk_bf16_f32 v87, v2, v3
	v_add_u32_e32 v2, v162, v148
	ds_write_b128 v2, v[84:87]
	global_load_dwordx4 v[36:39], v[220:221], off offset:2048
	s_and_saveexec_b64 s[40:41], s[10:11]
	s_cbranch_execz .LBB0_838
	v_cvt_pk_bf16_f32 v0, v0, 0
	v_mov_b32_e32 v3, v1
	v_mov_b32_e32 v2, v0
	ds_write_b128 v162, v[0:3] offset:128
	ds_write_b128 v162, v[0:3] offset:144

; #define LAS __attribute__((address_space(3)))
; __global__ void __launch_bounds__(512, 2) fwd_megakernel(Args args) {
;     extern __shared__ __attribute__((aligned(16))) unsigned char lds_raw[];
;     LAS unsigned char* lds = (LAS unsigned char*)lds_raw;
	.amdhsa_kernel _Z14fwd_megakernel4Args
		.amdhsa_group_segment_fixed_size 0
		.amdhsa_private_segment_fixed_size 0
		.amdhsa_kernarg_size 456
		.amdhsa_user_sgpr_count 2
		.amdhsa_user_sgpr_dispatch_ptr 0
		.amdhsa_user_sgpr_queue_ptr 0
		.amdhsa_user_sgpr_kernarg_segment_ptr 1
		.amdhsa_user_sgpr_dispatch_id 0
		.amdhsa_user_sgpr_kernarg_preload_length 0
		.amdhsa_user_sgpr_kernarg_preload_offset 0
		.amdhsa_user_sgpr_private_segment_size 0
		.amdhsa_uses_dynamic_stack 0
		.amdhsa_enable_private_segment 0
		.amdhsa_system_sgpr_workgroup_id_x 1
		.amdhsa_system_sgpr_workgroup_id_y 0
		.amdhsa_system_sgpr_workgroup_id_z 0
		.amdhsa_system_sgpr_workgroup_info 0
		.amdhsa_system_vgpr_workitem_id 2
		.amdhsa_next_free_vgpr 256
		.amdhsa_next_free_sgpr 102
		.amdhsa_accum_offset 256
		.amdhsa_reserve_vcc 1
		.amdhsa_float_round_mode_32 0
		.amdhsa_float_round_mode_16_64 0
		.amdhsa_float_denorm_mode_32 3
		.amdhsa_float_denorm_mode_16_64 3
		.amdhsa_dx10_clamp 1
		.amdhsa_ieee_mode 1
		.amdhsa_fp16_overflow 0
		.amdhsa_tg_split 0
		.amdhsa_exception_fp_ieee_invalid_op 0
		.amdhsa_exception_fp_denorm_src 0
		.amdhsa_exception_fp_ieee_div_zero 0
		.amdhsa_exception_fp_ieee_overflow 0
		.amdhsa_exception_fp_ieee_underflow 0
		.amdhsa_exception_fp_ieee_inexact 0
		.amdhsa_exception_int_div_zero 0
	.end_amdhsa_kernel

; #define LAS __attribute__((address_space(3)))
; __global__ void __launch_bounds__(512, 2) fwd_megakernel(Args args) {
;     extern __shared__ __attribute__((aligned(16))) unsigned char lds_raw[];
;     LAS unsigned char* lds = (LAS unsigned char*)lds_raw;
amdhsa.kernels:
  - .agpr_count:     0
    .args:
      - .offset:         0
        .size:           200
        .value_kind:     by_value
      - .offset:         200
        .size:           4
        .value_kind:     hidden_block_count_x
      - .offset:         204
        .size:           4
        .value_kind:     hidden_block_count_y
      - .offset:         208
        .size:           4
        .value_kind:     hidden_block_count_z
      - .offset:         212
        .size:           2
        .value_kind:     hidden_group_size_x
      - .offset:         214
        .size:           2
        .value_kind:     hidden_group_size_y
      - .offset:         216
        .size:           2
        .value_kind:     hidden_group_size_z
      - .offset:         218
        .size:           2
        .value_kind:     hidden_remainder_x
      - .offset:         220
        .size:           2
        .value_kind:     hidden_remainder_y
      - .offset:         222
        .size:           2
        .value_kind:     hidden_remainder_z
      - .offset:         240
        .size:           8
        .value_kind:     hidden_global_offset_x
      - .offset:         248
        .size:           8
        .value_kind:     hidden_global_offset_y
      - .offset:         256
        .size:           8
        .value_kind:     hidden_global_offset_z
      - .offset:         264
        .size:           2
        .value_kind:     hidden_grid_dims
      - .offset:         288
        .size:           8
        .value_kind:     hidden_multigrid_sync_arg
      - .offset:         320
        .size:           4
        .value_kind:     hidden_dynamic_lds_size
    .group_segment_fixed_size: 0
    .kernarg_segment_align: 8
    .kernarg_segment_size: 456
    .language:       OpenCL C
    .language_version:
      - 2
      - 0
    .max_flat_workgroup_size: 512
    .name:           _Z14fwd_megakernel4Args
    .private_segment_fixed_size: 0
    .sgpr_count:     108
    .sgpr_spill_count: 131
    .symbol:         _Z14fwd_megakernel4Args.kd
    .uniform_work_group_size: 1
    .uses_dynamic_stack: false
    .vgpr_count:     256
    .vgpr_spill_count: 0
    .wavefront_size: 64
